# P4 task-table cost weights NSA:DSA 11:10 (NSA steps got cheaper after pipelining)
# speedup vs baseline: 1.0045x; 1.0025x over previous
; __global__ void __launch_bounds__(NTHR, 2) fwd_kernel(Args a) {
;     ...
;             for (int k = lane; k < 96; k += 64) {
;                 const int cost = k < 32 ? 7 * ((k + 1) + (k + 1 < 9 ? k + 1 : 9)) : 6 * (((k - 32) >> 1) + 1), cnt = k < 32 ? 32 : 16; int pos = 0;
;                 for (int k2 = 0; k2 < 96; ++k2) { const int c2 = k2 < 32 ? 7 * ((k2 + 1) + (k2 + 1 < 9 ? k2 + 1 : 9)) : 6 * (((k2 - 32) >> 1) + 1), n2 = k2 < 32 ? 32 : 16;
;                     if (c2 > cost || (c2 == cost && k2 < k)) pos += n2; }
;                 for (int bb = 0; bb < cnt; ++bb) TASKTAB[pos + bb] = (unsigned)k | ((unsigned)bb << 8);
.LBB0_159:
	v_cmp_lt_u32_e32 vcc, 31, v2
	s_and_saveexec_b64 s[4:5], vcc
	s_xor_b64 s[4:5], exec, s[4:5]
	v_subrev_u32_e32 v1, 32, v2
	v_lshrrev_b32_e32 v1, 1, v1
	v_mad_u64_u32 v[4:5], s[6:7], v1, 10, 10
	s_or_saveexec_b64 s[4:5], s[4:5]
	v_mov_b32_e32 v6, 16
	s_xor_b64 exec, exec, s[4:5]
	v_add_u32_e32 v1, 1, v2
	v_min_u32_e32 v3, 9, v1
	v_add_u32_e32 v1, v3, v1
	v_mul_lo_u32 v4, v1, 11
	v_mov_b32_e32 v6, 32
	s_or_b64 exec, exec, s[4:5]
	s_and_b64 s[4:5], exec, vcc
	s_or_b64 s[22:23], s[4:5], s[22:23]
	v_mov_b32_e32 v3, v4
	v_mov_b32_e32 v1, v2
	s_mov_b32 s21, 1
	v_mov_b32_e32 v7, 0
	s_movk_i32 s30, 0x60
	s_mov_b32 s31, 0
	v_mov_b32_e32 v5, 0
.LBB0_164:
	s_sub_i32 s6, s31, 32
	s_sub_i32 s7, s21, 32
	s_add_i32 s8, s21, 1
	s_add_i32 s9, s31, 1
	s_lshr_b32 s7, s7, 1
	s_lshr_b32 s6, s6, 1
	s_min_u32 s10, s9, 9
	s_min_u32 s11, s8, 9
	s_mul_i32 s6, s6, 10
	s_mul_i32 s7, s7, 10
	s_add_i32 s8, s11, s8
	s_add_i32 s9, s10, s9
	s_add_i32 s7, s7, 10
	s_add_i32 s6, s6, 10
	s_mul_i32 s9, s9, 11
	s_cmp_lt_u32 s31, 32
	s_mul_i32 s8, s8, 11
	s_cselect_b32 s10, 32, 16
	s_cselect_b32 s9, s9, s6
	s_cmp_lt_u32 s21, 32
	v_cmp_ge_u32_e32 vcc, s31, v2
	s_cselect_b32 s12, s8, s7
	v_cmp_le_i32_e64 s[6:7], s9, v4
	v_cmp_ne_u32_e64 s[8:9], s9, v4
	s_cselect_b32 s33, 32, 16
	s_sub_i32 s40, s21, 30
	s_sub_i32 s41, s31, 30
	s_or_b64 s[34:35], s[8:9], vcc
	v_cmp_ge_u32_e64 s[4:5], s21, v1
	v_mov_b32_e32 v8, s10
	s_add_i32 s46, s31, 3
	s_add_i32 s47, s21, 3
	v_cmp_le_i32_e64 s[10:11], s12, v3
	v_cmp_ne_u32_e64 s[12:13], s12, v3
	v_mov_b32_e32 v9, s33
	s_lshr_b32 s33, s41, 1
	s_lshr_b32 s40, s40, 1
	s_and_b64 s[6:7], s[6:7], s[34:35]
	s_min_u32 s41, s47, 9
	s_min_u32 s48, s46, 9
	s_or_b64 s[4:5], s[12:13], s[4:5]
	v_cndmask_b32_e64 v8, v8, 0, s[6:7]
	s_mul_i32 s6, s40, 10
	s_mul_i32 s7, s33, 10
	s_add_i32 s36, s31, 2
	s_add_i32 s37, s21, 2
	s_add_i32 s12, s48, s46
	s_add_i32 s13, s41, s47
	s_and_b64 s[4:5], s[10:11], s[4:5]
	s_add_i32 s7, s7, 10
	s_add_i32 s6, s6, 10
	s_mul_i32 s13, s13, 11
	s_cmp_lt_u32 s37, 32
	s_mul_i32 s12, s12, 11
	s_cselect_b32 s10, 32, 16
	s_cselect_b32 s6, s13, s6
	s_cmp_lt_u32 s36, 32
	v_cmp_ge_u32_e32 vcc, s37, v1
	v_cndmask_b32_e64 v9, v9, 0, s[4:5]
	s_cselect_b32 s33, 32, 16
	s_cselect_b32 s12, s12, s7
	v_cmp_le_i32_e64 s[4:5], s6, v3
	v_cmp_ne_u32_e64 s[6:7], s6, v3
	s_sub_i32 s40, s21, 28
	s_sub_i32 s41, s31, 28
	v_cmp_ge_u32_e64 s[8:9], s36, v2
	v_add_u32_e32 v7, v7, v8
	v_add_u32_e32 v5, v5, v9
	v_mov_b32_e32 v8, s10
	s_add_i32 s46, s31, 5
	s_add_i32 s47, s21, 5
	v_cmp_le_i32_e64 s[10:11], s12, v4
	v_cmp_ne_u32_e64 s[12:13], s12, v4
	s_or_b64 s[34:35], s[6:7], vcc
	v_mov_b32_e32 v9, s33
	s_lshr_b32 s33, s41, 1
	s_lshr_b32 s40, s40, 1
	s_min_u32 s41, s47, 9
	s_min_u32 s48, s46, 9
	s_or_b64 s[8:9], s[12:13], s[8:9]
	s_and_b64 s[4:5], s[4:5], s[34:35]
	s_mul_i32 s12, s40, 10
	s_mul_i32 s13, s33, 10
	s_add_i32 s36, s31, 4
	s_add_i32 s37, s21, 4
	v_cndmask_b32_e64 v8, v8, 0, s[4:5]
	s_add_i32 s33, s48, s46
	s_add_i32 s34, s41, s47
	s_and_b64 s[4:5], s[10:11], s[8:9]
	s_add_i32 s13, s13, 10
	s_add_i32 s12, s12, 10
	s_mul_i32 s34, s34, 11
	s_cmp_lt_u32 s37, 32
	s_mul_i32 s33, s33, 11
	s_cselect_b32 s10, 32, 16
	s_cselect_b32 s8, s34, s12
	s_cmp_lt_u32 s36, 32
	v_cmp_ge_u32_e32 vcc, s37, v1
	v_cndmask_b32_e64 v9, v9, 0, s[4:5]
	s_cselect_b32 s12, s33, s13
	v_cmp_le_i32_e64 s[4:5], s8, v3
	v_cmp_ne_u32_e64 s[8:9], s8, v3
	v_cmp_ge_u32_e64 s[6:7], s36, v2
	s_cselect_b32 s34, 32, 16
	v_mov_b32_e32 v10, s10
	v_cmp_le_i32_e64 s[10:11], s12, v4
	v_cmp_ne_u32_e64 s[12:13], s12, v4
	s_or_b64 s[8:9], s[8:9], vcc
	s_or_b64 s[6:7], s[12:13], s[6:7]
	s_and_b64 s[4:5], s[4:5], s[8:9]
	v_mov_b32_e32 v11, s34
	v_cndmask_b32_e64 v10, v10, 0, s[4:5]
	s_and_b64 s[4:5], s[10:11], s[6:7]
	s_add_i32 s31, s31, 6
	s_add_i32 s21, s21, 6
	s_add_i32 s30, s30, -6
	v_cndmask_b32_e64 v11, v11, 0, s[4:5]
	v_add3_u32 v5, v5, v8, v10
	s_cmp_lg_u32 s30, 0
	v_add3_u32 v7, v7, v9, v11
	s_cbranch_scc1 .LBB0_164
	v_add_u32_e32 v4, v7, v5
	v_ashrrev_i32_e32 v5, 31, v4
	v_lshl_add_u64 v[4:5], v[4:5], 2, s[42:43]
	s_mov_b32 s6, 1
	s_mov_b32 s7, 0
	s_mov_b64 s[4:5], 0
